# SSD scan: waves 4-7 start stage b 8 sleep-quanta later (out of phase with SIMD partner); HG chains staggered by two barriers
# speedup vs baseline: 1.0061x; 1.0061x over previous
; #define LAS __attribute__((address_space(3)))
; DI void ssd_dma(LAS unsigned char* lds, const MixL& P, size_t rowbase, int b, int g, int c, int tid, int wave) {
;     const int t0 = c * 64;
;     { const int cgi = tid & 31, run = tid >> 5;
;       const int c0 = 256 * g + 8 * cgi;
; #pragma unroll
;       for (int j = 0; j < 4; ++j) __builtin_amdgcn_global_load_lds((const unsigned*)(P.XA + (rowbase + t0 + 4 * run + j) * 768 + c0), (LAS unsigned*)(lds + SSD_STG + j * 8192 + wave * 1024), 16, 0, 0); }
;     if (wave < 4) { const int run = (tid & 127) >> 3;
;       const int c0 = (wave < 2 ? 512 : 640) + 64 * g + 8 * (tid & 7);
; #pragma unroll
;       for (int j = 0; j < 4; ++j) __builtin_amdgcn_global_load_lds((const unsigned*)(P.XA + (rowbase + t0 + 4 * run + j) * 768 + c0), (LAS unsigned*)(lds + SSD_STG + 32768 + j * 4096 + wave * 1024), 16, 0, 0);
;       __builtin_amdgcn_global_load_lds((const unsigned*)(P.DTA + (size_t)(b * 32 + c) * 2048 + wave * 512 + (4 * g + ((tid & 63) >> 4)) * 64 + 4 * (tid & 15)), (LAS unsigned*)(lds + SSD_DT2 + wave * 1024), 16, 0, 0); }
; DI void ssd_unit(LAS unsigned char* lds, const MixL& P, int b, int g) {
;     ...
;         __syncthreads();
;         u32x2 zr[2][4];
; #pragma unroll
;         for (int pt = 0; pt < 2; ++pt)
; #pragma unroll
;             for (int ti = 0; ti < 4; ++ti) zr[pt][ti] = *(const u32x2*)(P.proj + (rowbase + t0 + 16 * ti + l15) * PL + ycol + 16 * pt);
;         if (c + 1 < SEQ / 64) ssd_dma(lds, P, rowbase, b, g, c + 1, tid, wave);
.LBB0_510:
	s_waitcnt lgkmcnt(0)
	v_lshl_add_u64 v[4:5], v[180:181], 0, v[176:177]
	v_add_co_u32_e32 v6, vcc, 0x1b000000, v4
	s_waitcnt vmcnt(8)
	s_nop 0
	v_addc_co_u32_e32 v7, vcc, 0, v5, vcc
	v_add_co_u32_e32 v46, vcc, 0x1b01c000, v4
	s_barrier
	s_cmp_lg_u64 s[40:41], 0
	s_cbranch_scc1 .Lssd_nosleep
	s_sleep 8
.Lssd_nosleep:
	s_nop 0
	v_addc_co_u32_e32 v47, vcc, 0, v5, vcc
	v_add_co_u32_e32 v48, vcc, 0x1b038000, v4
	s_nop 1
	v_addc_co_u32_e32 v49, vcc, 0, v5, vcc
	v_add_co_u32_e32 v4, vcc, 0x1b054000, v4
	s_cmp_eq_u32 s70, 0x2e8000
	s_nop 0
	v_addc_co_u32_e32 v5, vcc, 0, v5, vcc
	global_load_dwordx2 v[196:197], v[6:7], off
	global_load_dwordx2 v[192:193], v[46:47], off
	global_load_dwordx2 v[190:191], v[46:47], off offset:32
	global_load_dwordx2 v[194:195], v[6:7], off offset:32
	global_load_dwordx2 v[188:189], v[48:49], off
	global_load_dwordx2 v[184:185], v[4:5], off
	global_load_dwordx2 v[182:183], v[4:5], off offset:32
	global_load_dwordx2 v[186:187], v[48:49], off offset:32
	s_cbranch_scc1 .LBB0_513
	v_lshl_add_u64 v[4:5], v[174:175], 0, s[70:71]
	s_mov_b64 s[4:5], 0x18000
	s_mov_b32 m0, s1
	v_lshl_add_u64 v[6:7], v[4:5], 0, s[4:5]
	s_mov_b64 s[4:5], 0x18600
	global_load_lds_dwordx4 v[6:7], off
	v_lshl_add_u64 v[6:7], v[4:5], 0, s[4:5]
	s_mov_b32 m0, s56
	s_mov_b64 s[4:5], 0x18c00
	global_load_lds_dwordx4 v[6:7], off
	v_lshl_add_u64 v[6:7], v[4:5], 0, s[4:5]
	s_mov_b32 m0, s81
	v_lshl_add_u64 v[4:5], v[4:5], 0, s[98:99]
	global_load_lds_dwordx4 v[6:7], off
	s_mov_b32 m0, s96
	s_and_b64 vcc, exec, s[24:25]
	global_load_lds_dwordx4 v[4:5], off
	s_cbranch_vccnz .LBB0_513
	v_lshl_add_u64 v[4:5], v[172:173], 0, s[70:71]
	s_mov_b64 s[4:5], 0x18000
	v_lshl_add_u64 v[6:7], v[4:5], 0, s[4:5]
	s_add_i32 m0, s0, 0x1a000
	s_mov_b64 s[4:5], 0x18600
	global_load_lds_dwordx4 v[6:7], off
	v_lshl_add_u64 v[6:7], v[4:5], 0, s[4:5]
	s_add_i32 m0, s0, 0x1b000
	s_mov_b64 s[4:5], 0x18c00
	global_load_lds_dwordx4 v[6:7], off
	v_lshl_add_u64 v[6:7], v[4:5], 0, s[4:5]
	s_add_i32 m0, s0, 0x1c000
	s_ashr_i32 s69, s68, 31
	global_load_lds_dwordx4 v[6:7], off
	v_lshl_add_u64 v[4:5], v[4:5], 0, s[98:99]
	s_add_i32 m0, s0, 0x1d000
	s_lshl_b64 s[24:25], s[68:69], 13
	global_load_lds_dwordx4 v[4:5], off
	v_lshl_add_u64 v[4:5], v[170:171], 0, s[24:25]
	s_add_i32 m0, s0, 0x1e000
	s_nop 0
	global_load_lds_dwordx4 v[4:5], off

; #define LAS __attribute__((address_space(3)))
; DI void hg_unit(LAS unsigned char* lds, const MixL& P, int pi) {
;     int tid_l = threadIdx.x; asm volatile("" : "+v"(tid_l));
;     const int tid = tid_l, lane = tid & 63, wave = __builtin_amdgcn_readfirstlane(tid >> 6), l15 = lane & 15, q = lane >> 4;
;     const int chain = wave >> 2, wv = wave & 3, ci = 2 * pi + chain, b = ci >> 3, h = ci & 7;
;     LAS unsigned char* base = lds + chain * 40960;
;     LAS unsigned char* QE = base; LAS unsigned char* KE = base + 9216; LAS unsigned char* KET = base + 18432; LAS unsigned char* VT = base + 27648;
;     LAS float* EBREF = (LAS float*)(base + 36864); LAS float* EBLR = EBREF + 64; LAS float* EBLAST = EBREF + 128; LAS float* CUMQ = EBREF + 192; LAS float* SSQP = EBREF + 448;
;     const int d = lane, tq = wv;
;     const float lb = P.lb[64 * h + d], oml = 1.0f - lb;
;     const size_t rowbase = (size_t)b * SEQ;
;     const int ycol = 64 * h + 16 * wv + 4 * q;
;     f32x4 SD[4];
; #pragma unroll
;     for (int i = 0; i < 4; ++i) SD[i] = (f32x4){0.f, 0.f, 0.f, 0.f};
;     const f32x4 nw = *(const f32x4*)(P.hg_nw + 16 * wv + 4 * q);
;     hg_dma(lds, P, rowbase, h, 0, tid, wave);
.LBB0_521:
	s_cmp_lt_i32 s73, 64
	s_cbranch_scc1 .LBB0_495
	v_mov_b32_e32 v9, v200
	s_lshl_b32 s0, s73, 1
	v_readfirstlane_b32 s10, v9
	s_ashr_i32 s33, s10, 8
	s_add_i32 s0, s0, s33
	s_addk_i32 s0, 0xff80
	s_lshl_b32 s1, s0, 6
	v_and_b32_e32 v18, 63, v9
	s_and_b32 s11, s1, 0x1c0
	s_ashr_i32 s20, s0, 3
	v_or_b32_e32 v0, s11, v18
	v_readlane_b32 s4, v254, 61
	s_ashr_i32 s12, s10, 6
	s_mul_i32 s1, s33, 0xa000
	s_ashr_i32 s21, s20, 31
	v_lshlrev_b32_e32 v0, 2, v0
	v_readlane_b32 s5, v254, 62
	v_lshrrev_b32_e32 v3, 2, v9
	s_and_b32 s13, s12, 3
	s_add_i32 s14, s1, 0
	s_lshl_b64 s[0:1], s[20:21], 11
	v_lshlrev_b32_e32 v6, 1, v9
	global_load_dword v122, v0, s[4:5]
	v_mov_b64_e32 v[0:1], s[64:65]
	s_lshl_b32 s46, s13, 4
	s_lshl_b32 s15, s13, 6
	v_readlane_b32 s4, v254, 63
	v_and_or_b32 v3, v3, 62, s0
	v_and_b32_e32 v22, 14, v6
	s_add_u32 s6, s4, s15
	v_readlane_b32 s0, v255, 0
	v_mad_u64_u32 v[6:7], s[8:9], v3, s27, v[0:1]
	v_lshlrev_b32_e32 v4, 4, v9
	s_addc_u32 s7, s0, 0
	s_lshl_b32 s38, s11, 1
	v_mad_i32_i24 v7, s1, v207, v7
	v_mov_b32_e32 v5, v8
	v_bfe_u32 v10, v9, 3, 3
	v_and_b32_e32 v4, 0x70, v4
	s_and_b32 s0, s10, 0xfffff00
	v_lshl_add_u64 v[6:7], v[6:7], 0, s[38:39]
	s_lshl_b32 s8, s12, 10
	s_add_i32 s12, 0, 0x14000
	v_or_b32_e32 v10, s0, v10
	v_lshl_add_u64 v[4:5], v[6:7], 0, v[4:5]
	s_mov_b64 s[0:1], 0xa00
	s_add_i32 s16, 0, 0x16000
	s_add_i32 m0, s12, s8
	s_add_i32 s24, s8, 0
	v_lshl_add_u64 v[6:7], v[4:5], 0, s[0:1]
	s_mov_b64 s[0:1], 0x2600
	s_add_i32 s25, s24, 0x18000
	v_or_b32_e32 v24, s15, v10
	v_lshl_add_u64 v[10:11], v[4:5], 0, s[0:1]
	s_mov_b64 s[0:1], 0xe00
	global_load_lds_dwordx4 v[6:7], off
	s_add_i32 m0, s16, s8
	s_add_i32 s38, s24, 0x1a000
	v_lshl_add_u64 v[12:13], v[4:5], 0, s[0:1]
	s_mov_b64 s[0:1], 0x2a00
	global_load_lds_dwordx4 v[10:11], off
	s_mov_b32 m0, s25
	s_add_i32 s40, s24, 0x1c000
	v_lshl_add_u64 v[14:15], v[4:5], 0, s[0:1]
	s_mov_b64 s[0:1], 0x1200
	global_load_lds_dwordx4 v[12:13], off
	s_mov_b32 m0, s38
	v_and_b32_e32 v2, 48, v9
	s_add_i32 s41, s24, 0x1e000
	v_lshl_add_u64 v[16:17], v[4:5], 0, s[0:1]
	s_mov_b64 s[0:1], 0x2e00
	global_load_lds_dwordx4 v[14:15], off
	s_mov_b32 m0, s40
	global_load_dwordx4 v[0:3], v2, s[6:7]
	v_lshl_add_u64 v[4:5], v[4:5], 0, s[0:1]
	global_load_lds_dwordx4 v[16:17], off
	s_mov_b32 m0, s41
	v_lshlrev_b32_e32 v7, 4, v24
	global_load_lds_dwordx4 v[4:5], off
	v_readlane_b32 s1, v254, 37
	v_mov_b32_e32 v23, s14
	s_movk_i32 s0, 0x90
	v_add_u32_e32 v12, s1, v7
	v_readlane_b32 s1, v254, 38
	v_bfe_u32 v19, v9, 4, 2
	v_lshl_add_u32 v123, v18, 2, s14
	v_add_u32_e32 v13, s1, v7
	v_readlane_b32 s1, v254, 39
	s_lshl_b32 s17, s13, 8
	v_lshl_add_u32 v4, v18, 1, s14
	v_add_u32_e32 v14, s1, v7
	v_readlane_b32 s1, v254, 40
	v_mad_u32_u24 v126, v18, s0, v23
	v_mul_i32_i24_e32 v5, 0xffffff74, v18
	v_add_u32_e32 v15, s1, v7
	v_readlane_b32 s1, v254, 41
	v_cmp_gt_u32_e64 s[10:11], 16, v18
	v_and_b32_e32 v20, 15, v9
	v_add_u32_e32 v16, s1, v7
	v_readlane_b32 s1, v254, 42
	v_lshlrev_b32_e32 v21, 2, v19
	s_cmp_eq_u32 s13, 0
	v_add_u32_e32 v17, s1, v7
	v_readlane_b32 s1, v254, 43
	v_lshlrev_b32_e32 v127, 3, v19
	v_lshl_add_u32 v124, v20, 2, s14
	v_add_u32_e32 v18, s1, v7
	v_readlane_b32 s1, v254, 44
	s_cselect_b64 s[22:23], -1, 0
	s_cmp_eq_u32 s13, 1
	v_add_u32_e32 v19, s1, v7
	v_readlane_b32 s1, v254, 45
	v_or_b32_e32 v30, 2, v21
	v_add_u32_e32 v125, s17, v123
	v_add_u32_e32 v24, s1, v7
	v_readlane_b32 s1, v254, 46
	s_cselect_b64 s[6:7], -1, 0
	s_cmp_eq_u32 s13, 2
	v_or_b32_e32 v6, s46, v20
	v_add_u32_e32 v129, s17, v124
	v_add_u32_e32 v11, s16, v7
	v_add_u32_e32 v25, s1, v7
	v_readlane_b32 s1, v254, 47
	v_cmp_gt_u32_e64 s[16:17], v30, v20
	v_or_b32_e32 v30, 3, v21
	s_cselect_b64 s[8:9], -1, 0
	v_mad_u32_u24 v6, v6, s0, v23
	v_add_u32_e32 v26, s1, v7
	v_readlane_b32 s1, v254, 48
	v_cmp_gt_u32_e64 s[18:19], v30, v20
	v_mad_u32_u24 v23, v20, s0, v23
	v_bfe_u32 v30, v9, 3, 5
	s_add_i32 s0, s72, s33
	v_add_u32_e32 v27, s1, v7
	v_readlane_b32 s1, v254, 49
	s_mul_i32 s49, s20, 0xe00000
	v_mul_hi_u32_u24_e32 v31, 0x3800, v30
	v_mul_u32_u24_e32 v30, 0x3800, v30
	s_and_b32 s33, s0, 7
	v_and_b32_e32 v9, 7, v9
	v_add_u32_e32 v28, s1, v7
	v_readlane_b32 s1, v254, 50
	v_or_b32_e32 v30, s49, v30
	s_lshl_b32 s0, s33, 7
	v_lshlrev_b32_e32 v9, 4, v9
	v_add_u32_e32 v10, s12, v7
	v_add_u32_e32 v7, s1, v7
	s_mul_hi_i32 s48, s20, 0xe00000
	v_or3_b32 v92, v30, s0, v9
	s_lshl_b64 s[0:1], s[20:21], 22
	s_lshl_b32 s20, s33, 6
	s_or_b32 s20, s20, s46
	s_lshl_b32 s52, s13, 5
	v_add_u32_e32 v128, s14, v127
	s_mul_i32 s47, s13, 0x900
	v_cmp_gt_u32_e64 s[12:13], v21, v20
	v_cmp_lt_u32_e64 s[14:15], v21, v20
	v_or_b32_e32 v21, s20, v21
	v_lshlrev_b32_e32 v9, 11, v20
	v_lshlrev_b32_e32 v21, 1, v21
	v_mul_u32_u24_e32 v29, 0x90, v20
	v_or3_b32 v94, s0, v9, v21
	v_mul_hi_u32_u24_e32 v9, 0x1c00, v20
	v_mul_u32_u24_e32 v20, 0x1c00, v20
	s_waitcnt vmcnt(0)
	v_sub_f32_e32 v90, 1.0, v122
	v_or_b32_e32 v97, s48, v9
	v_or_b32_e32 v9, s49, v20
	v_mov_b32_e32 v98, 0
	v_mov_b32_e32 v91, v90
	v_or_b32_e32 v93, s48, v31
	v_mov_b32_e32 v95, s1
	v_or_b32_e32 v96, v9, v21
	s_mov_b32 s53, 32
	v_add_u32_e32 v130, v10, v22
	v_add_u32_e32 v131, v11, v22
	v_add_u32_e32 v132, v12, v22
	v_add_u32_e32 v133, v13, v22
	v_add_u32_e32 v134, v14, v22
	v_add_u32_e32 v135, v15, v22
	v_add_u32_e32 v136, v16, v22
	v_add_u32_e32 v137, v17, v22
	v_add_u32_e32 v138, v18, v22
	v_add_u32_e32 v139, v19, v22
	v_add_u32_e32 v140, v24, v22
	v_add_u32_e32 v141, v25, v22
	v_add_u32_e32 v142, v26, v22
	v_add_u32_e32 v143, v27, v22
	v_add_u32_e32 v144, v28, v22
	v_add_u32_e32 v145, v7, v22
	v_add_u32_e32 v146, s47, v4
	v_add_u32_e32 v147, v126, v5
	v_add_u32_e32 v148, v128, v29
	v_add_u32_e32 v149, v6, v127
	v_add_u32_e32 v150, v23, v127
	v_mov_b32_e32 v99, v98
	v_mov_b32_e32 v100, v98
	v_mov_b32_e32 v101, v98
	v_mov_b32_e32 v102, v98
	v_mov_b32_e32 v103, v98
	v_mov_b32_e32 v104, v98
	v_mov_b32_e32 v105, v98
	v_mov_b32_e32 v106, v98
	v_mov_b32_e32 v107, v98
	v_mov_b32_e32 v108, v98
	v_mov_b32_e32 v109, v98
	v_mov_b32_e32 v110, v98
	v_mov_b32_e32 v111, v98
	v_mov_b32_e32 v112, v98
	v_mov_b32_e32 v113, v98
	v_readfirstlane_b32 s0, v200
	s_nop 3
	s_lshr_b32 s0, s0, 8
	s_cmp_eq_u32 s0, 0
	s_cbranch_scc1 .LBB0_524
	s_barrier
	s_barrier
	s_branch .LBB0_524
